# v16: v15 + entry stagger of odd-local-index workgroups within each XCD at all GEMM phase entries (G_WIN 4us, ATTUP 6us, G_OUT/MLPOUT/PLE 12us, MLPIN 4us)
# baseline (speedup 1.0000x reference)
;     __host__ __device__ bool next(int i, Unit& u) const {
;         const long L = (long)i * G + c; if (L >= nwg) return false;
;         int wgid = (int)L; { const int q = nwg / NXCD, r = nwg % NXCD, xcd = wgid % NXCD, off = wgid / NXCD; wgid = (xcd < r ? xcd * (q + 1) : r * (q + 1) + (xcd - r) * q) + off; }
;         const int nig = WGM * nN, gid = wgid / nig, fm = gid * WGM, gsz = (nM - fm) < WGM ? (nM - fm) : WGM;
;         u.pm = fm + ((wgid % nig) % gsz); u.pn = (wgid % nig) / gsz; return true;
; __global__ void __launch_bounds__(NWAVES * 64, 2) mk_fwd(Args args) {
;     ...
;     if (IN(G_WIN)) {
;         {
;             pg8::Gemm g{(const bf16*)(ws + WS_X8), (const bf16*)(ws + WS_WIN8), M, NQKV, D / 2, D / 2, D / 2, 0}; pg8::StaticOrder S; S.init(M, NQKV, F.G, bx);
;             pg8::EpiWin8 E{(bf16*)(ws + WS_QKV), (bf16*)(ws + WS_Z), (bf16*)(ws + WS_GT), RSTD, (const float*)(ws + WS_SX), (const float*)(ws + WS_SW), 0};
;             pg8::gemm_phase<pg8::EpiWin8, pg8::StaticOrder, true, true, true>(F.lds + RING_OFF, g, S, E);
.LBB0_471:
	s_cmp_lt_i32 s4, 2
	s_cselect_b64 s[0:1], -1, 0
	s_cmp_gt_i32 s5, 1
	s_cselect_b64 s[2:3], -1, 0
	s_and_b64 s[0:1], s[0:1], s[2:3]
	s_andn2_b64 vcc, exec, s[0:1]
	s_cbranch_vccnz .LBB0_708
	v_readlane_b32 s98, v254, 3
	s_bitcmp1_b32 s98, 3
	s_cbranch_scc0 .Lstg_gwin
	s_sleep 127
.Lstg_gwin:
	v_readlane_b32 s0, v254, 3
	s_cmpk_lt_i32 s0, 0x480
	s_cselect_b64 s[2:3], -1, 0
	s_cmpk_gt_i32 s0, 0x47f
	v_readfirstlane_b32 s4, v0
	v_readlane_b32 s1, v254, 4
	s_cbranch_scc1 .LBB0_474
	v_readlane_b32 s0, v254, 3
	s_mov_b32 s6, s0
	s_ashr_i32 s0, s0, 31
	s_lshr_b32 s0, s0, 29
	v_readlane_b32 s1, v254, 4
	s_add_i32 s0, s6, s0
	s_ashr_i32 s1, s0, 3
	s_and_b32 s0, s0, -8
	s_sub_i32 s0, s6, s0
	s_cmp_lt_i32 s0, 0
	s_movk_i32 s5, 0x91
	s_cselect_b32 s5, s5, 0x90
	s_mul_i32 s0, s0, s5
	s_add_i32 s0, s0, s1
	s_mul_hi_i32 s1, s0, 0x38e38e39
	s_lshr_b32 s5, s1, 31
	s_ashr_i32 s1, s1, 5
	s_add_i32 s1, s1, s5
	s_lshl_b32 s5, s1, 3
	s_mulk_i32 s1, 0x90
	s_sub_i32 s0, s0, s1
	s_sext_i32_i16 s1, s0
	s_bfe_u32 s1, s1, 0x3001c
	s_add_i32 s1, s0, s1
	s_sext_i32_i16 s7, s1
	s_and_b32 s1, s1, 0xfff8
	s_sub_i32 s0, s0, s1
	s_sext_i32_i16 s0, s0
	s_add_i32 s6, s5, s0
	s_ashr_i32 s30, s7, 3

;     __host__ __device__ bool next(int i, Unit& u) const {
;         const long L = (long)i * G + c; if (L >= nwg) return false;
;         int wgid = (int)L; { const int q = nwg / NXCD, r = nwg % NXCD, xcd = wgid % NXCD, off = wgid / NXCD; wgid = (xcd < r ? xcd * (q + 1) : r * (q + 1) + (xcd - r) * q) + off; }
; __global__ void __launch_bounds__(NWAVES * 64, 2) mk_fwd(Args args) {
;     ...
;     if (IN(G_ATTUP)) {
;         pg8::Gemm g{(const bf16*)(ws + WS_ATT), (const bf16*)(ws + WS_WATT), M, D, AOW, AOW, AOW, 0}; pg8::StaticOrder S; S.init(M, D, F.G, bx);
;         pg8::EpiB<2> E{(bf16*)(ws + WS_AD), D, nullptr, (const bf16*)(ws + WS_GT), nullptr, nullptr};
;         pg8::gemm_phase<pg8::EpiB<2>, pg8::StaticOrder, true, true>(F.lds + RING_OFF, g, S, E);
.LBB0_1520:
	s_cmp_lt_i32 s4, 8
	s_cselect_b64 s[0:1], -1, 0
	s_cmp_gt_i32 s5, 7
	s_cselect_b64 s[2:3], -1, 0
	s_and_b64 s[0:1], s[0:1], s[2:3]
	s_andn2_b64 vcc, exec, s[0:1]
	s_cbranch_vccnz .LBB0_1545
	v_readlane_b32 s98, v254, 3
	s_bitcmp1_b32 s98, 3
	s_cbranch_scc0 .Lstg_attup
	s_sleep 100
	s_sleep 100
.Lstg_attup:
	v_readlane_b32 s0, v254, 3
	s_cmpk_gt_i32 s0, 0x3ff
	v_readfirstlane_b32 s5, v0
	v_readlane_b32 s1, v254, 4
	s_cbranch_scc1 .LBB0_1545
	v_readlane_b32 s0, v254, 3
	s_ashr_i32 s28, s0, 31
	s_mov_b32 s2, s0
	s_lshr_b32 s0, s28, 29
	s_add_i32 s3, s2, s0
	s_and_b32 s0, s3, -8
	s_sub_i32 s4, s2, s0
	s_cmp_gt_i32 s4, -1
	v_readlane_b32 s1, v254, 4
	s_cbranch_scc0 .LBB0_1524
	s_lshl_b32 s2, s4, 7
	s_cbranch_execz .LBB0_1525
	s_branch .LBB0_1526

; #define GRID_BAR() xcd_barrier(bar)
; #define GRID_BAR() do {} while (0)
; __global__ void __launch_bounds__(NWAVES * 64, 2) mk_fwd(Args args) {
;     ...
;     if (IN(G_OUT)) {
;         rows_bf16_to_i8(F, (const bf16*)(ws + WS_MERGED), (const unsigned*)(ws + CTL_RMAX3), (unsigned*)(ws + WS_X8C), (float*)(ws + WS_SX3));
;         GRID_BAR();
;         pg8::Gemm g{(const bf16*)(ws + WS_X8C), (const bf16*)(ws + WS_W8O), M, D, D / 2, D / 2, D / 2, 0}; pg8::StaticOrder S; S.init(M, D, F.G, bx);
;         pg8::EpiF<0, true> E{F.in[0], F.out, nullptr, nullptr, XB, (float*)(ws + CTL_SS2), (unsigned*)(ws + CTL_RMAX2), (const float*)(ws + WS_SX3), (const float*)(ws + WS_SWO)};
;         pg8::gemm_phase<pg8::EpiF<0, true>, pg8::StaticOrder, true, true, true>(F.lds + RING_OFF, g, S, E);
.LBB0_1702:
	s_or_b64 exec, exec, s[0:1]
	v_readlane_b32 s98, v254, 3
	s_bitcmp1_b32 s98, 3
	s_cbranch_scc0 .Lstg_gout
	s_sleep 112
	s_sleep 112
	s_sleep 112
	s_sleep 112
.Lstg_gout:
	v_readlane_b32 s0, v254, 3
	v_readlane_b32 s1, v254, 4
	s_mov_b32 s2, s0
	s_cmpk_lt_i32 s0, 0x400
	s_cselect_b64 s[0:1], -1, 0
	s_cmpk_gt_i32 s2, 0x3ff
	v_readfirstlane_b32 s4, v0
	s_waitcnt lgkmcnt(0)
	s_barrier
	s_cbranch_scc1 .LBB0_1708
	v_readlane_b32 s2, v254, 3
	s_mov_b32 s6, s2
	s_ashr_i32 s2, s2, 31
	s_lshr_b32 s2, s2, 29
	s_add_i32 s5, s6, s2
	s_and_b32 s2, s5, -8
	s_sub_i32 s6, s6, s2
	s_cmp_gt_i32 s6, -1
	v_readlane_b32 s3, v254, 4
	s_cbranch_scc0 .LBB0_1705
	s_lshl_b32 s7, s6, 7
	s_cbranch_execz .LBB0_1706
	s_branch .LBB0_1707

; __global__ void __launch_bounds__(NWAVES * 64, 2) mk_fwd(Args args) {
;     ...
;     if (IN(G_MLPIN)) {
;         pg8::Gemm g{(const bf16*)(ws + WS_X8B), (const bf16*)(ws + WS_W8M), M, DFF, D / 2, D / 2, D / 2, 0}; pg8::StaticOrder S; S.init(M, DFF, F.G, bx);
;         pg8::EpiMlp8 E{(bf16*)(ws + WS_HID), DFF, (const float*)(ws + CTL_SS2), (const float*)(ws + WS_SX2), (const float*)(ws + WS_SWM)};
;         pg8::gemm_phase<pg8::EpiMlp8, pg8::StaticOrder, true, true, true>(F.lds + RING_OFF, g, S, E);
.LBB0_1996:
	s_cmp_lt_i32 s72, 12
	s_cselect_b64 s[0:1], -1, 0
	s_cmp_gt_i32 s73, 11
	s_cselect_b64 s[2:3], -1, 0
	s_and_b64 s[0:1], s[0:1], s[2:3]
	s_andn2_b64 vcc, exec, s[0:1]
	v_readlane_b32 s70, v254, 6
	v_readlane_b32 s71, v254, 7
	s_cbranch_vccnz .LBB0_2075
	v_readlane_b32 s98, v254, 3
	s_bitcmp1_b32 s98, 3
	s_cbranch_scc0 .Lstg_mlpin
	s_sleep 127
.Lstg_mlpin:
	v_readlane_b32 s0, v254, 3
	s_cmpk_gt_i32 s0, 0xfff
	v_readfirstlane_b32 s5, v0
	v_readlane_b32 s1, v254, 4
	s_cbranch_scc1 .LBB0_2021
	v_readlane_b32 s0, v254, 3
	s_ashr_i32 s33, s0, 31
	s_mov_b32 s2, s0
	s_lshr_b32 s0, s33, 29
	s_add_i32 s3, s2, s0
	s_and_b32 s0, s3, -8
	s_sub_i32 s4, s2, s0
	s_cmp_gt_i32 s4, -1
	v_readlane_b32 s1, v254, 4
	s_cbranch_scc0 .LBB0_2000
	s_lshl_b32 s2, s4, 9
	s_cbranch_execz .LBB0_2001
	s_branch .LBB0_2002

; __global__ void __launch_bounds__(NWAVES * 64, 2) mk_fwd(Args args) {
;     ...
;     if (IN(G_MLPOUT)) {
;         pg8::Gemm g{(const bf16*)(ws + WS_HID), (const bf16*)(ws + WS_WMLPOUT), M, D, DFF, DFF, DFF, 0}; pg8::StaticOrder S; S.init(M, D, F.G, bx);
;         pg8::EpiF<0> E{F.out, F.out, nullptr, nullptr, XB, (float*)(ws + CTL_SS3), (unsigned*)(ws + CTL_RMAX4), nullptr, nullptr};
;         pg8::gemm_phase<pg8::EpiF<0>, pg8::StaticOrder, true, true>(F.lds + RING_OFF, g, S, E);
.LBB0_2075:
	s_cmp_lt_i32 s72, 13
	s_cselect_b64 s[0:1], -1, 0
	s_cmp_gt_i32 s73, 12
	s_cselect_b64 s[2:3], -1, 0
	s_and_b64 s[0:1], s[0:1], s[2:3]
	s_andn2_b64 vcc, exec, s[0:1]
	s_cbranch_vccnz .LBB0_2220
	v_readlane_b32 s98, v254, 3
	s_bitcmp1_b32 s98, 3
	s_cbranch_scc0 .Lstg_mlpout
	s_sleep 112
	s_sleep 112
	s_sleep 112
	s_sleep 112
.Lstg_mlpout:
	v_readlane_b32 s0, v254, 3
	v_readlane_b32 s1, v254, 4
	s_mov_b32 s2, s0
	s_cmpk_lt_i32 s0, 0x400
	s_cselect_b64 s[0:1], -1, 0
	s_cmpk_gt_i32 s2, 0x3ff
	v_readfirstlane_b32 s4, v0
	s_cbranch_scc1 .LBB0_2079
	v_readlane_b32 s2, v254, 3
	s_mov_b32 s6, s2
	s_ashr_i32 s2, s2, 31
	s_lshr_b32 s2, s2, 29
	s_add_i32 s5, s6, s2
	s_and_b32 s2, s5, -8
	s_sub_i32 s6, s6, s2
	s_cmp_gt_i32 s6, -1
	v_readlane_b32 s3, v254, 4
	s_cbranch_scc0 .LBB0_2163
	s_lshl_b32 s7, s6, 7
	s_cbranch_execz .LBB0_2164
	s_branch .LBB0_2165

; __global__ void __launch_bounds__(NWAVES * 64, 2) mk_fwd(Args args) {
;     ...
;     if (IN(G_PLE)) {
;         pg8::Gemm g{(const bf16*)(ws + WS_X8D), (const bf16*)(ws + WS_W8P), M, D, D / 2, D / 2, D / 2, 0}; pg8::StaticOrder S; S.init(M, D, F.G, bx);
;         pg8::EpiF<1, true> E{F.out, F.out, (const float*)(ws + CTL_SS3), (const bf16*)(ws + WS_PP), nullptr, nullptr, nullptr, (const float*)(ws + WS_SX4), (const float*)(ws + WS_SWP)};
;         pg8::gemm_phase<pg8::EpiF<1, true>, pg8::StaticOrder, true, true, true>(F.lds + RING_OFF, g, S, E);
.LBB0_2304:
	s_cmp_lt_i32 s72, 15
	s_cselect_b64 s[0:1], -1, 0
	s_cmp_gt_i32 s73, 14
	s_cselect_b64 s[2:3], -1, 0
	s_and_b64 s[0:1], s[0:1], s[2:3]
	s_andn2_b64 vcc, exec, s[0:1]
	s_cbranch_vccnz .LBB0_2329
	v_readlane_b32 s98, v254, 3
	s_bitcmp1_b32 s98, 3
	s_cbranch_scc0 .Lstg_ple
	s_sleep 112
	s_sleep 112
	s_sleep 112
	s_sleep 112
.Lstg_ple:
	v_readlane_b32 s0, v254, 3
	s_cmpk_gt_i32 s0, 0x3ff
	v_readfirstlane_b32 s16, v0
	v_readlane_b32 s1, v254, 4
	s_cbranch_scc1 .LBB0_2329
	v_readlane_b32 s0, v254, 3
	s_ashr_i32 s33, s0, 31
	s_mov_b32 s2, s0
	s_lshr_b32 s0, s33, 29
	s_add_i32 s4, s2, s0
	s_and_b32 s0, s4, -8
	s_sub_i32 s3, s2, s0
	s_cmp_gt_i32 s3, -1
	v_readlane_b32 s1, v254, 4
	s_cbranch_scc0 .LBB0_2308
	s_lshl_b32 s2, s3, 7
	s_ashr_i32 s0, s4, 3
	s_cbranch_execz .LBB0_2309
	s_branch .LBB0_2310
